# static priority raise (s_setprio 1) for waves 4-7 during the attention phase, reset at its end
# speedup vs baseline: 1.0025x; 1.0025x over previous
.LBB0_221:
	v_writelane_b32 v250, s71, 23
	v_writelane_b32 v250, s70, 24
	v_writelane_b32 v250, s68, 25
	s_nop 1
	v_writelane_b32 v250, s69, 26
	v_writelane_b32 v250, s66, 27
	s_nop 1
	v_writelane_b32 v250, s67, 28
	s_or_b64 exec, exec, s[0:1]
	s_add_u32 s50, s82, 0x26000000
	s_addc_u32 s51, s83, 0
	s_add_u32 s67, s82, 0xa000000
	s_addc_u32 s68, s83, 0
	s_waitcnt lgkmcnt(0)
	v_mov_b32_e32 v0, v194
	s_add_u32 s69, s82, 0x8000000
	s_barrier
	s_addc_u32 s70, s83, 0
	v_readfirstlane_b32 s0, v0
	s_ashr_i32 s0, s0, 6
	s_cmp_lt_u32 s0, 4
	s_cbranch_scc1 .Lattn_prio_done
	s_setprio 1
.Lattn_prio_done:
	s_mul_i32 s1, s0, 0x1080
	s_add_i32 s1, s1, 0
	v_and_b32_e32 v180, 63, v0
	s_add_i32 s4, s1, 0x12840
	s_add_i32 s71, s0, s64
	v_and_b32_e32 v169, 16, v0
	s_mov_b32 s73, 0
	s_cmpk_gt_i32 s65, 0xff
	v_bfe_u32 v179, v180, 2, 2
	v_lshrrev_b32_e32 v178, 3, v180
	v_lshlrev_b32_e32 v182, 3, v180
	v_and_b32_e32 v181, 60, v180
	s_cbranch_scc1 .LBB0_295
	v_writelane_b32 v250, s76, 29
	v_lshrrev_b32_e32 v1, 5, v180
	v_lshlrev_b32_e32 v189, 2, v1
	v_writelane_b32 v250, s77, 30
	v_writelane_b32 v250, s78, 31
	v_writelane_b32 v250, s79, 32
	v_writelane_b32 v250, s80, 33
	v_writelane_b32 v250, s81, 34
	v_lshrrev_b32_e32 v2, 2, v0
	v_writelane_b32 v250, s82, 35
	v_ashrrev_i32_e32 v184, 4, v0
	s_movk_i32 s1, 0x110
	v_and_or_b32 v2, v2, 3, v189
	v_writelane_b32 v250, s83, 36
	v_mul_lo_u32 v185, v184, s1
	s_movk_i32 s1, 0x140
	v_mul_u32_u24_e32 v190, 0x140, v2
	v_lshlrev_b32_e32 v2, 2, v0
	v_and_b32_e32 v183, 31, v0
	v_and_b32_e32 v3, 15, v0
	v_mul_lo_u32 v187, v184, s1
	v_and_or_b32 v2, v2, 12, v169
	v_lshlrev_b32_e32 v0, 6, v0
	v_readlane_b32 s2, v250, 21
	s_lshl_b32 s1, s0, 2
	v_lshlrev_b32_e32 v162, 4, v1
	v_lshlrev_b32_e32 v191, 1, v2
	v_lshlrev_b32_e32 v2, 3, v1
	v_and_b32_e32 v0, 0x3c0, v0
	v_mov_b32_e32 v1, 0
	v_readlane_b32 s3, v250, 22
	s_add_i32 s93, s1, 0
	v_writelane_b32 v250, s4, 37
	s_lshl_b32 s1, s0, 11
	s_lshl_b32 s33, s0, 5
	v_lshl_add_u64 v[4:5], s[2:3], 0, v[0:1]
	s_add_i32 s93, s93, 0x12800
	v_readlane_b32 s2, v250, 19
	s_and_b32 s1, s1, 0x2000
	v_readlane_b32 s3, v250, 20
	s_cmp_gt_i32 s0, 5
	v_writelane_b32 v250, s1, 38
	v_lshl_add_u64 v[6:7], s[2:3], 0, v[0:1]
	v_or_b32_e32 v0, 8, v189
	s_cselect_b64 s[2:3], -1, 0
	s_add_u32 s40, s46, 0x4000
	v_cmp_lt_u32_e64 s[14:15], v0, v183
	v_or_b32_e32 v0, 9, v189
	s_addc_u32 s41, s47, 0
	v_cmp_lt_u32_e64 s[16:17], v0, v183
	v_or_b32_e32 v0, 10, v189
	v_writelane_b32 v250, s2, 39
	s_cmp_eq_u32 s0, 7
	v_cmp_lt_u32_e64 s[18:19], v0, v183
	v_or_b32_e32 v0, 11, v189
	v_writelane_b32 v250, s3, 40
	s_cselect_b64 s[2:3], -1, 0
	v_lshlrev_b32_e32 v192, 3, v3
	v_cmp_lt_u32_e64 s[20:21], v0, v183
	v_or_b32_e32 v0, 17, v189
	v_writelane_b32 v250, s2, 41
	s_cmp_eq_u32 s0, 6
	v_lshlrev_b32_e32 v186, 4, v3
	v_lshlrev_b32_e32 v3, 5, v184
	v_and_b32_e32 v164, 24, v192
	s_movk_i32 s75, 0x1e0
	v_cmp_lt_u32_e64 s[24:25], v0, v183
	v_or_b32_e32 v0, 18, v189
	v_writelane_b32 v250, s3, 42
	s_cselect_b64 s[0:1], -1, 0
	v_and_or_b32 v166, v3, s75, v164
	v_lshlrev_b32_e32 v3, 2, v180
	v_and_b32_e32 v195, 24, v182
	v_mov_b32_e32 v163, v1
	v_cmp_lt_u32_e64 s[26:27], v0, v183
	v_or_b32_e32 v0, 19, v189
	v_writelane_b32 v250, s0, 43
	v_and_b32_e32 v168, 28, v3
	v_mul_u32_u24_e32 v3, 0x84, v195
	v_lshl_add_u64 v[170:171], v[4:5], 0, v[162:163]
	v_or_b32_e32 v4, 1, v189
	v_cmp_lt_u32_e64 s[28:29], v0, v183
	v_or_b32_e32 v0, 25, v189
	v_writelane_b32 v250, s1, 44
	v_add3_u32 v196, s4, v3, v181
	v_bitop3_b32 v3, v178, 12, 8 bitop3:0xc8
	v_cmp_lt_u32_e64 s[8:9], v4, v183
	v_or_b32_e32 v4, 2, v189
	v_cmp_lt_u32_e64 s[34:35], v0, v183
	v_or_b32_e32 v0, 26, v189
	v_writelane_b32 v250, s84, 45
	v_lshl_add_u32 v16, v168, 2, s4
	v_mul_u32_u24_e32 v17, 0x84, v178
	v_and_or_b32 v8, v178, 4, v179
	v_or3_b32 v197, v169, v3, v179
	v_mov_b32_e32 v3, v1
	v_cmp_lt_u32_e64 s[10:11], v4, v183
	v_or_b32_e32 v4, 3, v189
	v_cmp_lt_u32_e64 s[36:37], v0, v183
	v_or_b32_e32 v0, 27, v189
	v_writelane_b32 v250, s85, 46
	s_lshl_b32 s0, s84, 5
	v_mov_b32_e32 v14, v1
	v_mov_b32_e32 v15, v1
	v_or_b32_e32 v198, 16, v189
	v_or_b32_e32 v199, 24, v189
	v_cmp_lt_u32_e64 s[12:13], v4, v183
	v_cmp_lt_u32_e64 s[38:39], v0, v183
	v_lshl_add_u64 v[172:173], v[6:7], 0, v[2:3]
	v_lshl_or_b32 v163, v8, 5, v195
	v_writelane_b32 v250, s0, 47
	v_mov_b32_e32 v0, v1
	v_mov_b32_e32 v2, v1
	v_mov_b32_e32 v4, v1
	v_mov_b32_e32 v5, v1
	v_mov_b32_e32 v6, v1
	v_mov_b32_e32 v7, v1
	v_mov_b32_e32 v8, v1
	v_mov_b32_e32 v9, v1
	v_mov_b32_e32 v10, v1
	v_mov_b32_e32 v11, v1
	v_mov_b32_e32 v12, v1
	v_mov_b32_e32 v13, v1
	v_add_u32_e32 v206, v16, v17
	v_mov_b64_e32 v[30:31], v[14:15]
	v_mul_u32_u24_e32 v188, 0x110, v183
	v_add_u32_e32 v193, 32, v184
	v_cmp_gt_u32_e64 s[42:43], 32, v180
	v_cmp_eq_u32_e64 s[4:5], 0, v180
	v_cmp_lt_u32_e64 s[6:7], v189, v183
	v_cmp_lt_u32_e64 s[22:23], v198, v183
	v_cmp_lt_u32_e64 s[30:31], v199, v183
	v_add_u32_e32 v200, 0x60, v184
	s_lshl_b32 s1, s65, 5
	v_lshlrev_b32_e32 v201, 3, v184
	s_add_i32 s74, s33, 0xffffff60
	s_movk_i32 s66, 0xff80
	v_writelane_b32 v250, s33, 48
	s_add_i32 s3, s33, 0xffffff80
	s_movk_i32 s97, 0x80
	s_mov_b32 s88, 0xc3300000
	v_mov_b32_e32 v202, 0x4400
	v_mov_b32_e32 v203, 0xc00
	v_mov_b32_e32 v204, 0x4000
	v_mbcnt_hi_u32_b32 v205, -1, v167
	v_mov_b64_e32 v[28:29], v[12:13]
	v_mov_b64_e32 v[26:27], v[10:11]
	v_mov_b64_e32 v[24:25], v[8:9]
	v_mov_b64_e32 v[22:23], v[6:7]
	v_mov_b64_e32 v[20:21], v[4:5]
	v_mov_b64_e32 v[18:19], v[2:3]
	v_mov_b64_e32 v[16:17], v[0:1]
	v_writelane_b32 v250, s65, 49
	s_branch .LBB0_224

.LBB0_302:
	s_setprio 0
	s_waitcnt vmcnt(0)
	s_waitcnt lgkmcnt(0)
	s_barrier
	s_mov_b64 s[0:1], exec
	v_readlane_b32 s2, v250, 0
	v_readlane_b32 s3, v250, 1
	v_readlane_b32 s54, v250, 21
	s_and_b64 s[2:3], s[0:1], s[2:3]
	v_readlane_b32 s64, v250, 24
	v_readlane_b32 s66, v250, 23
	v_readlane_b32 s71, v250, 18
	v_readlane_b32 s55, v250, 22
	s_mov_b64 exec, s[2:3]
	s_cbranch_execz .LBB0_354
	s_add_i32 s2, 0, 0x23ff0
	v_mov_b32_e32 v0, s2
	s_waitcnt vmcnt(0) expcnt(0) lgkmcnt(0)
	ds_read_b32 v2, v0
	s_add_i32 s2, 0, 0x23ff4
	v_mov_b32_e32 v0, s2
	ds_read_b32 v0, v0
	s_waitcnt lgkmcnt(1)
	v_cmp_ne_u32_e32 vcc, 0, v2
	s_cbranch_vccnz .LBB0_318
	s_add_u32 s4, s82, 0x2a100200
	s_addc_u32 s5, s83, 0
	s_add_u32 s6, s82, 0x2a100400
	s_addc_u32 s7, s83, 0
	s_add_u32 s8, s82, 0x2a100500
	s_addc_u32 s9, s83, 0
	s_add_u32 s10, s82, 0x2a100600
	s_addc_u32 s11, s83, 0
	s_add_u32 s12, s82, 0x2a100700
	s_addc_u32 s13, s83, 0
	s_add_u32 s14, s82, 0x2a100800
	s_addc_u32 s15, s83, 0
	s_add_u32 s16, s82, 0x2a100900
	s_addc_u32 s17, s83, 0
	s_add_u32 s18, s82, 0x2a100a00
	s_addc_u32 s19, s83, 0
	s_add_u32 s20, s82, 0x2a100b00
	s_addc_u32 s21, s83, 0
	s_add_u32 s22, s82, 0x2a100c00
	s_addc_u32 s23, s83, 0
	s_add_u32 s24, s82, 0x2a100d00
	s_addc_u32 s25, s83, 0
	s_add_u32 s26, s82, 0x2a100e00
	s_addc_u32 s27, s83, 0
	s_add_u32 s28, s82, 0x2a100f00
	s_addc_u32 s29, s83, 0
	s_add_u32 s30, s82, 0x2a101000
	s_addc_u32 s31, s83, 0
	s_add_u32 s34, s82, 0x2a101100
	s_addc_u32 s35, s83, 0
	s_add_u32 s36, s82, 0x2a101200
	s_addc_u32 s37, s83, 0
	s_mul_i32 s2, s85, s66
	s_add_u32 s38, s82, 0x2a101300
	s_mul_i32 s2, s2, s84
	s_addc_u32 s39, s83, 0
	s_mov_b32 s3, 1
	v_mov_b32_e32 v16, 0
	s_branch .LBB0_306
